# v25 + phase-12 epilogue: c1/c2 loads issued before the statistics-table barrier
# baseline (speedup 1.0000x reference)
; #define LAS __attribute__((address_space(3)))
; #define GASP __attribute__((address_space(1)))
; __device__ __forceinline__ float silu_f(float g) { return g * frcp(1.f + fexp2(-g * LOG2E)); }
; __device__ __forceinline__ void row_stats_table(LAS unsigned char* lds, const float* ST, int pm) {
;     ...
;     asm volatile("s_waitcnt lgkmcnt(0)" ::: "memory"); __builtin_amdgcn_s_barrier(); asm volatile("" ::: "memory");
; }
; template <bool PERM>
; __device__ __forceinline__ void ln_fold_fix(Acc& acc, const Unit& u, int wr, int wc, int fr, int fq, const float* c1, const float* c2, LAS unsigned char* lds) {
;     const LAS f32x2* SL = (const LAS f32x2*)(lds + SL_OFF);
; #pragma unroll
;     for (int bj = 0; bj < 2; ++bj)
; #pragma unroll
;         for (int n = 0; n < 2; ++n) { const int c = u.pn * BM + bj * HALF + wc * 32 + (PERM ? 8 * fq + 4 * n : 16 * n + 4 * fq);
;             const f32x4 a1 = *(const GASP f32x4*)(c1 + c), a2 = *(const GASP f32x4*)(c2 + c);
; #pragma unroll
;             for (int ai = 0; ai < 2; ++ai)
; #pragma unroll
;                 for (int m = 0; m < 4; ++m) { const f32x2 st = SL[ai * HALF + wr * 64 + m * 16 + fr]; acc[ai][bj][m][n] = (acc[ai][bj][m][n] - a1 * st[0]) * st[1] + a2; } }
;     __device__ __forceinline__ void operator()(Acc& acc, const Unit& u, int wr, int wc, int fr, int fq, LAS unsigned char* lds) const {
;     ...
;                 const f32x4 g0 = acc[ai][0][m][0], g1 = acc[ai][0][m][1], u0 = acc[ai][1][m][0], u1 = acc[ai][1][m][1];
;                 u32x4 w;
;                 w.x = pk2(silu_f(g0[0]) * u0[0], silu_f(g0[1]) * u0[1]); w.y = pk2(silu_f(g0[2]) * u0[2], silu_f(g0[3]) * u0[3]);
;                 w.z = pk2(silu_f(g1[0]) * u1[0], silu_f(g1[1]) * u1[1]); w.w = pk2(silu_f(g1[2]) * u1[2], silu_f(g1[3]) * u1[3]);
.LBB0_1573:
	s_or_b64 exec, exec, s[34:35]
	s_lshl_b32 s10, s67, 8
	s_or_b32 s10, s10, s60
	v_or_b32_e32 v154, s10, v145
	s_bitset1_b32 s10, 7
	v_or_b32_e32 v170, s10, v145
	v_ashrrev_i32_e32 v155, 31, v154
	v_ashrrev_i32_e32 v171, 31, v170
	v_lshlrev_b64 v[162:163], 2, v[154:155]
	v_lshlrev_b64 v[174:175], 2, v[170:171]
	v_lshl_add_u64 v[158:159], s[14:15], 0, v[162:163]
	v_lshl_add_u64 v[166:167], s[16:17], 0, v[162:163]
	v_lshl_add_u64 v[170:171], s[14:15], 0, v[174:175]
	global_load_dwordx4 v[154:157], v[158:159], off
	s_nop 0
	global_load_dwordx4 v[158:161], v[158:159], off offset:16
	s_nop 0
	global_load_dwordx4 v[162:165], v[166:167], off
	s_nop 0
	global_load_dwordx4 v[166:169], v[166:167], off offset:16
	v_lshl_add_u64 v[190:191], s[16:17], 0, v[174:175]
	global_load_dwordx4 v[170:173], v[170:171], off
	v_or_b32_e32 v198, s10, v147
	global_load_dwordx4 v[174:177], v[190:191], off
	v_ashrrev_i32_e32 v199, 31, v198
	v_lshl_add_u64 v[202:203], v[198:199], 2, s[14:15]
	global_load_dwordx4 v[198:201], v[190:191], off offset:16
	s_nop 0
	global_load_dwordx4 v[202:205], v[202:203], off
	s_waitcnt lgkmcnt(0)
	s_barrier
	ds_read2_b64 v[178:181], v153 offset1:16
	ds_read2_b64 v[182:185], v153 offset0:32 offset1:48
	ds_read2_b64 v[186:189], v153 offset0:128 offset1:144
	ds_read2_b64 v[194:197], v153 offset0:160 offset1:176
	s_andn2_b64 vcc, exec, s[8:9]
	s_mov_b64 s[8:9], -1
	s_waitcnt vmcnt(0)
	v_xor_b32_e32 v157, 0x80000000, v157
	v_xor_b32_e32 v156, 0x80000000, v156
	s_waitcnt lgkmcnt(3)
	v_pk_fma_f32 v[120:121], v[154:155], v[178:179], v[120:121] op_sel_hi:[1,0,1] neg_lo:[1,0,0] neg_hi:[1,0,0]
	v_pk_fma_f32 v[112:113], v[154:155], v[180:181], v[112:113] op_sel_hi:[1,0,1] neg_lo:[1,0,0] neg_hi:[1,0,0]
	s_waitcnt lgkmcnt(2)
	v_pk_fma_f32 v[104:105], v[154:155], v[182:183], v[104:105] op_sel_hi:[1,0,1] neg_lo:[1,0,0] neg_hi:[1,0,0]
	v_pk_fma_f32 v[96:97], v[154:155], v[184:185], v[96:97] op_sel_hi:[1,0,1] neg_lo:[1,0,0] neg_hi:[1,0,0]
	s_waitcnt lgkmcnt(1)
	v_pk_fma_f32 v[88:89], v[154:155], v[186:187], v[88:89] op_sel_hi:[1,0,1] neg_lo:[1,0,0] neg_hi:[1,0,0]
	v_pk_fma_f32 v[76:77], v[154:155], v[188:189], v[76:77] op_sel_hi:[1,0,1] neg_lo:[1,0,0] neg_hi:[1,0,0]
	s_waitcnt lgkmcnt(0)
	v_pk_fma_f32 v[68:69], v[154:155], v[194:195], v[68:69] op_sel_hi:[1,0,1] neg_lo:[1,0,0] neg_hi:[1,0,0]
	v_pk_fma_f32 v[60:61], v[154:155], v[196:197], v[60:61] op_sel_hi:[1,0,1] neg_lo:[1,0,0] neg_hi:[1,0,0]
	v_pk_fma_f32 v[154:155], v[182:183], v[158:159], v[108:109] op_sel_hi:[0,1,1] neg_lo:[1,0,0] neg_hi:[1,0,0]
	v_pk_fma_f32 v[72:73], v[180:181], v[170:171], v[72:73] op_sel_hi:[0,1,1] neg_lo:[1,0,0] neg_hi:[1,0,0]
	v_pk_fma_f32 v[216:217], v[156:157], v[182:183], v[106:107] op_sel_hi:[1,0,1]
	v_pk_fma_f32 v[106:107], v[182:183], v[154:155], v[166:167] op_sel:[1,0,0]
	v_pk_fma_f32 v[154:155], v[180:181], v[72:73], v[174:175] op_sel:[1,0,0]
	v_pk_fma_f32 v[66:67], v[182:183], v[172:173], v[66:67] op_sel_hi:[0,1,1] neg_lo:[1,0,0] neg_hi:[1,0,0]
	v_pk_fma_f32 v[72:73], v[182:183], v[170:171], v[64:65] op_sel_hi:[0,1,1] neg_lo:[1,0,0] neg_hi:[1,0,0]
	v_pk_fma_f32 v[116:117], v[180:181], v[158:159], v[116:117] op_sel_hi:[0,1,1] neg_lo:[1,0,0] neg_hi:[1,0,0]
	v_pk_fma_f32 v[122:123], v[156:157], v[178:179], v[122:123] op_sel_hi:[1,0,1]
	v_pk_fma_f32 v[64:65], v[182:183], v[66:67], v[176:177] op_sel:[1,0,0]
	v_pk_fma_f32 v[66:67], v[182:183], v[72:73], v[174:175] op_sel:[1,0,0]
	v_pk_fma_f32 v[58:59], v[184:185], v[172:173], v[58:59] op_sel_hi:[0,1,1] neg_lo:[1,0,0] neg_hi:[1,0,0]
	v_pk_fma_f32 v[72:73], v[184:185], v[170:171], v[56:57] op_sel_hi:[0,1,1] neg_lo:[1,0,0] neg_hi:[1,0,0]
	v_pk_fma_f32 v[212:213], v[156:157], v[180:181], v[114:115] op_sel_hi:[1,0,1]
	v_pk_fma_f32 v[114:115], v[180:181], v[116:117], v[166:167] op_sel:[1,0,0]
	v_pk_fma_f32 v[116:117], v[178:179], v[122:123], v[164:165] op_sel:[1,0,0]
	v_pk_fma_f32 v[50:51], v[194:195], v[160:161], v[50:51] op_sel_hi:[0,1,1] neg_lo:[1,0,0] neg_hi:[1,0,0]
	v_pk_fma_f32 v[122:123], v[194:195], v[158:159], v[48:49] op_sel_hi:[0,1,1] neg_lo:[1,0,0] neg_hi:[1,0,0]
	v_pk_fma_f32 v[56:57], v[184:185], v[58:59], v[176:177] op_sel:[1,0,0]
	v_pk_fma_f32 v[58:59], v[184:185], v[72:73], v[174:175] op_sel:[1,0,0]
	v_pk_fma_f32 v[34:35], v[186:187], v[172:173], v[34:35] op_sel_hi:[0,1,1] neg_lo:[1,0,0] neg_hi:[1,0,0]
	v_pk_fma_f32 v[72:73], v[186:187], v[170:171], v[32:33] op_sel_hi:[0,1,1] neg_lo:[1,0,0] neg_hi:[1,0,0]
	v_pk_fma_f32 v[44:45], v[180:181], v[202:203], v[44:45] op_sel_hi:[0,1,1] neg_lo:[1,0,0] neg_hi:[1,0,0]
	v_pk_fma_f32 v[38:39], v[182:183], v[204:205], v[38:39] op_sel_hi:[0,1,1] neg_lo:[1,0,0] neg_hi:[1,0,0]
	v_pk_fma_f32 v[28:29], v[184:185], v[202:203], v[28:29] op_sel_hi:[0,1,1] neg_lo:[1,0,0] neg_hi:[1,0,0]
	v_pk_fma_f32 v[14:15], v[186:187], v[204:205], v[14:15] op_sel_hi:[0,1,1] neg_lo:[1,0,0] neg_hi:[1,0,0]
	v_pk_fma_f32 v[8:9], v[188:189], v[202:203], v[8:9] op_sel_hi:[0,1,1] neg_lo:[1,0,0] neg_hi:[1,0,0]
	v_pk_fma_f32 v[6:7], v[194:195], v[204:205], v[6:7] op_sel_hi:[0,1,1] neg_lo:[1,0,0] neg_hi:[1,0,0]
	v_pk_fma_f32 v[124:125], v[178:179], v[158:159], v[124:125] op_sel_hi:[0,1,1] neg_lo:[1,0,0] neg_hi:[1,0,0]
	v_pk_fma_f32 v[190:191], v[184:185], v[158:159], v[100:101] op_sel_hi:[0,1,1] neg_lo:[1,0,0] neg_hi:[1,0,0]
	v_pk_fma_f32 v[206:207], v[186:187], v[158:159], v[92:93] op_sel_hi:[0,1,1] neg_lo:[1,0,0] neg_hi:[1,0,0]
	v_pk_fma_f32 v[210:211], v[188:189], v[158:159], v[84:85] op_sel_hi:[0,1,1] neg_lo:[1,0,0] neg_hi:[1,0,0]
	v_pk_fma_f32 v[120:121], v[178:179], v[120:121], v[162:163] op_sel:[1,0,0]
	v_pk_fma_f32 v[48:49], v[194:195], v[50:51], v[168:169] op_sel:[1,0,0]
; #define GASP __attribute__((address_space(1)))
; __device__ __forceinline__ float silu_f(float g) { return g * frcp(1.f + fexp2(-g * LOG2E)); }
; template <bool PERM>
; __device__ __forceinline__ void ln_fold_fix(Acc& acc, const Unit& u, int wr, int wc, int fr, int fq, const float* c1, const float* c2, LAS unsigned char* lds) {
;     ...
;         for (int n = 0; n < 2; ++n) { const int c = u.pn * BM + bj * HALF + wc * 32 + (PERM ? 8 * fq + 4 * n : 16 * n + 4 * fq);
;             const f32x4 a1 = *(const GASP f32x4*)(c1 + c), a2 = *(const GASP f32x4*)(c2 + c);
; #pragma unroll
;             for (int ai = 0; ai < 2; ++ai)
; #pragma unroll
;                 for (int m = 0; m < 4; ++m) { const f32x2 st = SL[ai * HALF + wr * 64 + m * 16 + fr]; acc[ai][bj][m][n] = (acc[ai][bj][m][n] - a1 * st[0]) * st[1] + a2; } }
;     __device__ __forceinline__ void operator()(Acc& acc, const Unit& u, int wr, int wc, int fr, int fq, LAS unsigned char* lds) const {
;     ...
;             for (int m = 0; m < 4; ++m) {
;                 const f32x4 g0 = acc[ai][0][m][0], g1 = acc[ai][0][m][1], u0 = acc[ai][1][m][0], u1 = acc[ai][1][m][1];
;                 u32x4 w;
;                 w.x = pk2(silu_f(g0[0]) * u0[0], silu_f(g0[1]) * u0[1]); w.y = pk2(silu_f(g0[2]) * u0[2], silu_f(g0[3]) * u0[3]);
;                 w.z = pk2(silu_f(g1[0]) * u1[0], silu_f(g1[1]) * u1[1]); w.w = pk2(silu_f(g1[2]) * u1[2], silu_f(g1[3]) * u1[3]);
;                 *(GASP u32x4*)(O + (size_t)(row0 + ai * HALF + m * 16) * FF + col0) = w;
	v_pk_fma_f32 v[50:51], v[194:195], v[122:123], v[166:167] op_sel:[1,0,0]
	v_pk_fma_f32 v[122:123], v[196:197], v[158:159], v[40:41] op_sel_hi:[0,1,1] neg_lo:[1,0,0] neg_hi:[1,0,0]
	v_pk_fma_f32 v[32:33], v[186:187], v[34:35], v[176:177] op_sel:[1,0,0]
	v_pk_fma_f32 v[34:35], v[186:187], v[72:73], v[174:175] op_sel:[1,0,0]
	v_pk_fma_f32 v[26:27], v[188:189], v[172:173], v[26:27] op_sel_hi:[0,1,1] neg_lo:[1,0,0] neg_hi:[1,0,0]
	v_pk_fma_f32 v[72:73], v[188:189], v[170:171], v[24:25] op_sel_hi:[0,1,1] neg_lo:[1,0,0] neg_hi:[1,0,0]
	v_pk_fma_f32 v[158:159], v[180:181], v[44:45], v[198:199] op_sel:[1,0,0]
	v_pk_fma_f32 v[44:45], v[182:183], v[38:39], v[200:201] op_sel:[1,0,0]
	v_pk_fma_f32 v[38:39], v[184:185], v[28:29], v[198:199] op_sel:[1,0,0]
	v_pk_fma_f32 v[28:29], v[186:187], v[14:15], v[200:201] op_sel:[1,0,0]
	v_pk_fma_f32 v[14:15], v[188:189], v[8:9], v[198:199] op_sel:[1,0,0]
	v_pk_fma_f32 v[8:9], v[194:195], v[202:203], v[4:5] op_sel_hi:[0,1,1] neg_lo:[1,0,0] neg_hi:[1,0,0]
	v_pk_fma_f32 v[4:5], v[194:195], v[6:7], v[200:201] op_sel:[1,0,0]
	v_pk_fma_f32 v[2:3], v[196:197], v[204:205], v[2:3] op_sel_hi:[0,1,1] neg_lo:[1,0,0] neg_hi:[1,0,0]
	v_pk_fma_f32 v[6:7], v[196:197], v[202:203], v[0:1] op_sel_hi:[0,1,1] neg_lo:[1,0,0] neg_hi:[1,0,0]
	v_pk_fma_f32 v[42:43], v[196:197], v[160:161], v[42:43] op_sel_hi:[0,1,1] neg_lo:[1,0,0] neg_hi:[1,0,0]
	v_pk_fma_f32 v[74:75], v[180:181], v[172:173], v[74:75] op_sel_hi:[0,1,1] neg_lo:[1,0,0] neg_hi:[1,0,0]
	v_pk_fma_f32 v[24:25], v[188:189], v[26:27], v[176:177] op_sel:[1,0,0]
	v_pk_fma_f32 v[26:27], v[188:189], v[72:73], v[174:175] op_sel:[1,0,0]
	v_pk_fma_f32 v[22:23], v[194:195], v[172:173], v[22:23] op_sel_hi:[0,1,1] neg_lo:[1,0,0] neg_hi:[1,0,0]
	v_pk_fma_f32 v[72:73], v[194:195], v[170:171], v[20:21] op_sel_hi:[0,1,1] neg_lo:[1,0,0] neg_hi:[1,0,0]
	v_pk_fma_f32 v[52:53], v[178:179], v[202:203], v[52:53] op_sel_hi:[0,1,1] neg_lo:[1,0,0] neg_hi:[1,0,0]
	v_pk_fma_f32 v[0:1], v[196:197], v[2:3], v[200:201] op_sel:[1,0,0]
	v_pk_fma_f32 v[2:3], v[196:197], v[6:7], v[198:199] op_sel:[1,0,0]
	v_mul_f32_e32 v6, 0xbfb8aa3b, v120
	v_mul_f32_e32 v7, 0xbfb8aa3b, v121
	v_pk_fma_f32 v[40:41], v[196:197], v[42:43], v[168:169] op_sel:[1,0,0]
	v_pk_fma_f32 v[42:43], v[196:197], v[122:123], v[166:167] op_sel:[1,0,0]
	v_pk_fma_f32 v[122:123], v[180:181], v[74:75], v[176:177] op_sel:[1,0,0]
	v_pk_fma_f32 v[20:21], v[194:195], v[22:23], v[176:177] op_sel:[1,0,0]
	v_pk_fma_f32 v[22:23], v[194:195], v[72:73], v[174:175] op_sel:[1,0,0]
	v_pk_fma_f32 v[18:19], v[196:197], v[172:173], v[18:19] op_sel_hi:[0,1,1] neg_lo:[1,0,0] neg_hi:[1,0,0]
	v_pk_fma_f32 v[72:73], v[196:197], v[170:171], v[16:17] op_sel_hi:[0,1,1] neg_lo:[1,0,0] neg_hi:[1,0,0]
	v_pk_fma_f32 v[74:75], v[178:179], v[52:53], v[198:199] op_sel:[1,0,0]
	v_exp_f32_e32 v6, v6
	v_exp_f32_e32 v7, v7
	v_mul_f32_e32 v53, 0xbfb8aa3b, v116
	v_pk_fma_f32 v[16:17], v[196:197], v[18:19], v[176:177] op_sel:[1,0,0]
	v_pk_fma_f32 v[18:19], v[196:197], v[72:73], v[174:175] op_sel:[1,0,0]
	v_exp_f32_e32 v53, v53
	v_mul_f32_e32 v72, 0xbfb8aa3b, v117
	v_exp_f32_e32 v72, v72
	v_add_f32_e32 v6, 1.0, v6
	v_add_f32_e32 v7, 1.0, v7
	v_rcp_f32_e32 v6, v6
	v_rcp_f32_e32 v7, v7
	v_add_f32_e32 v53, 1.0, v53
	v_pk_fma_f32 v[126:127], v[178:179], v[160:161], v[126:127] op_sel_hi:[0,1,1] neg_lo:[1,0,0] neg_hi:[1,0,0]
	v_pk_fma_f32 v[118:119], v[180:181], v[160:161], v[118:119] op_sel_hi:[0,1,1] neg_lo:[1,0,0] neg_hi:[1,0,0]
	v_pk_fma_f32 v[110:111], v[182:183], v[160:161], v[110:111] op_sel_hi:[0,1,1] neg_lo:[1,0,0] neg_hi:[1,0,0]
	v_pk_fma_f32 v[102:103], v[184:185], v[160:161], v[102:103] op_sel_hi:[0,1,1] neg_lo:[1,0,0] neg_hi:[1,0,0]
	v_pk_fma_f32 v[94:95], v[186:187], v[160:161], v[94:95] op_sel_hi:[0,1,1] neg_lo:[1,0,0] neg_hi:[1,0,0]
	v_pk_fma_f32 v[86:87], v[188:189], v[160:161], v[86:87] op_sel_hi:[0,1,1] neg_lo:[1,0,0] neg_hi:[1,0,0]
	v_rcp_f32_e32 v160, v53
	v_add_f32_e32 v53, 1.0, v72
	v_pk_fma_f32 v[124:125], v[178:179], v[124:125], v[166:167] op_sel:[1,0,0]
	v_rcp_f32_e32 v161, v53
	v_pk_fma_f32 v[80:81], v[178:179], v[170:171], v[80:81] op_sel_hi:[0,1,1] neg_lo:[1,0,0] neg_hi:[1,0,0]
	v_mul_f32_e32 v53, 0xbfb8aa3b, v124
	v_pk_fma_f32 v[80:81], v[178:179], v[80:81], v[174:175] op_sel:[1,0,0]
	v_pk_mul_f32 v[6:7], v[120:121], v[6:7]
	v_exp_f32_e32 v53, v53
	v_mul_f32_e32 v73, 0xbfb8aa3b, v125
	v_pk_fma_f32 v[82:83], v[178:179], v[172:173], v[82:83] op_sel_hi:[0,1,1] neg_lo:[1,0,0] neg_hi:[1,0,0]
	v_pk_mul_f32 v[6:7], v[6:7], v[80:81]
	v_exp_f32_e32 v80, v73
	v_pk_fma_f32 v[82:83], v[178:179], v[82:83], v[176:177] op_sel:[1,0,0]
	v_cvt_pk_bf16_f32 v72, v6, v7
	v_pk_mul_f32 v[6:7], v[116:117], v[160:161]
	v_pk_fma_f32 v[126:127], v[178:179], v[126:127], v[168:169] op_sel:[1,0,0]
	v_pk_mul_f32 v[6:7], v[6:7], v[82:83]
	v_pk_fma_f32 v[54:55], v[178:179], v[204:205], v[54:55] op_sel_hi:[0,1,1] neg_lo:[1,0,0] neg_hi:[1,0,0]
	v_cvt_pk_bf16_f32 v73, v6, v7
	v_add_f32_e32 v6, 1.0, v53
	v_mul_f32_e32 v53, 0xbfb8aa3b, v126
	v_add_f32_e32 v7, 1.0, v80
	v_exp_f32_e32 v53, v53
	v_mul_f32_e32 v80, 0xbfb8aa3b, v127
	v_exp_f32_e32 v81, v80
	v_rcp_f32_e32 v6, v6
	v_rcp_f32_e32 v7, v7
	v_add_f32_e32 v53, 1.0, v53
	v_rcp_f32_e32 v80, v53
	v_add_f32_e32 v53, 1.0, v81
	v_rcp_f32_e32 v81, v53
	v_pk_mul_f32 v[6:7], v[124:125], v[6:7]
	v_pk_fma_f32 v[54:55], v[178:179], v[54:55], v[200:201] op_sel:[1,0,0]
	v_pk_mul_f32 v[6:7], v[74:75], v[6:7]
	v_pk_fma_f32 v[46:47], v[180:181], v[204:205], v[46:47] op_sel_hi:[0,1,1] neg_lo:[1,0,0] neg_hi:[1,0,0]
	v_pk_fma_f32 v[36:37], v[182:183], v[202:203], v[36:37] op_sel_hi:[0,1,1] neg_lo:[1,0,0] neg_hi:[1,0,0]
; #define GASP __attribute__((address_space(1)))
; __device__ __forceinline__ float silu_f(float g) { return g * frcp(1.f + fexp2(-g * LOG2E)); }
;     __device__ __forceinline__ void operator()(Acc& acc, const Unit& u, int wr, int wc, int fr, int fq, LAS unsigned char* lds) const {
;     ...
;         const int row0 = u.pm * BM + wr * 64 + fr, col0 = u.pn * 128 + wc * 32 + 8 * fq;
; #pragma unroll
;         for (int ai = 0; ai < 2; ++ai)
; #pragma unroll
;             for (int m = 0; m < 4; ++m) {
;                 const f32x4 g0 = acc[ai][0][m][0], g1 = acc[ai][0][m][1], u0 = acc[ai][1][m][0], u1 = acc[ai][1][m][1];
;                 u32x4 w;
;                 w.x = pk2(silu_f(g0[0]) * u0[0], silu_f(g0[1]) * u0[1]); w.y = pk2(silu_f(g0[2]) * u0[2], silu_f(g0[3]) * u0[3]);
;                 w.z = pk2(silu_f(g1[0]) * u1[0], silu_f(g1[1]) * u1[1]); w.w = pk2(silu_f(g1[2]) * u1[2], silu_f(g1[3]) * u1[3]);
;                 *(GASP u32x4*)(O + (size_t)(row0 + ai * HALF + m * 16) * FF + col0) = w;
	v_pk_fma_f32 v[30:31], v[184:185], v[204:205], v[30:31] op_sel_hi:[0,1,1] neg_lo:[1,0,0] neg_hi:[1,0,0]
	v_pk_fma_f32 v[12:13], v[186:187], v[202:203], v[12:13] op_sel_hi:[0,1,1] neg_lo:[1,0,0] neg_hi:[1,0,0]
	v_pk_fma_f32 v[10:11], v[188:189], v[204:205], v[10:11] op_sel_hi:[0,1,1] neg_lo:[1,0,0] neg_hi:[1,0,0]
	v_cvt_pk_bf16_f32 v74, v6, v7
	v_pk_mul_f32 v[6:7], v[126:127], v[80:81]
	v_pk_fma_f32 v[218:219], v[156:157], v[184:185], v[98:99] op_sel_hi:[1,0,1]
	v_pk_fma_f32 v[220:221], v[156:157], v[186:187], v[90:91] op_sel_hi:[1,0,1]
	v_pk_fma_f32 v[222:223], v[156:157], v[188:189], v[78:79] op_sel_hi:[1,0,1]
	v_pk_fma_f32 v[70:71], v[156:157], v[194:195], v[70:71] op_sel_hi:[1,0,1]
	v_pk_fma_f32 v[62:63], v[156:157], v[196:197], v[62:63] op_sel_hi:[1,0,1]
	v_pk_fma_f32 v[156:157], v[180:181], v[46:47], v[200:201] op_sel:[1,0,0]
	v_pk_fma_f32 v[46:47], v[182:183], v[36:37], v[198:199] op_sel:[1,0,0]
	v_pk_fma_f32 v[36:37], v[184:185], v[30:31], v[200:201] op_sel:[1,0,0]
	v_pk_fma_f32 v[30:31], v[186:187], v[12:13], v[198:199] op_sel:[1,0,0]
	v_pk_fma_f32 v[12:13], v[188:189], v[10:11], v[200:201] op_sel:[1,0,0]
	v_pk_fma_f32 v[10:11], v[194:195], v[8:9], v[198:199] op_sel:[1,0,0]
	v_lshl_or_b32 v8, s67, 7, v148
	v_pk_mul_f32 v[6:7], v[54:55], v[6:7]
	v_pk_fma_f32 v[214:215], v[180:181], v[112:113], v[162:163] op_sel:[1,0,0]
	v_add_u32_e32 v52, s25, v144
	v_ashrrev_i32_e32 v9, 31, v8
	v_cvt_pk_bf16_f32 v75, v6, v7
	v_mov_b64_e32 v[6:7], s[44:45]
	v_mad_i64_i32 v[54:55], s[10:11], v52, s66, v[6:7]
	v_lshlrev_b64 v[8:9], 1, v[8:9]
	v_mul_f32_e32 v53, 0xbfb8aa3b, v214
	v_pk_fma_f32 v[112:113], v[180:181], v[118:119], v[168:169] op_sel:[1,0,0]
	v_pk_fma_f32 v[118:119], v[180:181], v[212:213], v[164:165] op_sel:[1,0,0]
	v_lshl_add_u64 v[54:55], v[54:55], 0, v[8:9]
	v_exp_f32_e32 v53, v53
	v_mul_f32_e32 v80, 0xbfb8aa3b, v215
	v_exp_f32_e32 v80, v80
	global_store_dwordx4 v[54:55], v[72:75], off
	v_mul_f32_e32 v55, 0xbfb8aa3b, v118
	v_add_f32_e32 v53, 1.0, v53
	v_exp_f32_e32 v72, v55
	v_mul_f32_e32 v55, 0xbfb8aa3b, v119
	v_exp_f32_e32 v73, v55
	v_rcp_f32_e32 v54, v53
	v_add_f32_e32 v53, 1.0, v80
	v_rcp_f32_e32 v55, v53
	v_add_f32_e32 v53, 1.0, v72
	v_rcp_f32_e32 v74, v53
	v_add_f32_e32 v53, 1.0, v73
	v_rcp_f32_e32 v75, v53
	v_pk_mul_f32 v[54:55], v[214:215], v[54:55]
	v_mul_f32_e32 v53, 0xbfb8aa3b, v114
	v_pk_mul_f32 v[54:55], v[54:55], v[154:155]
	v_exp_f32_e32 v53, v53
	v_mul_f32_e32 v73, 0xbfb8aa3b, v115
	v_cvt_pk_bf16_f32 v72, v54, v55
	v_pk_mul_f32 v[54:55], v[118:119], v[74:75]
	v_exp_f32_e32 v74, v73
	v_pk_mul_f32 v[54:55], v[54:55], v[122:123]
	v_add_f32_e32 v53, 1.0, v53
	v_cvt_pk_bf16_f32 v73, v54, v55
	v_mul_f32_e32 v55, 0xbfb8aa3b, v112
	v_rcp_f32_e32 v54, v53
	v_add_f32_e32 v53, 1.0, v74
	v_exp_f32_e32 v74, v55
	v_mul_f32_e32 v55, 0xbfb8aa3b, v113
	v_exp_f32_e32 v75, v55
	v_rcp_f32_e32 v55, v53
	v_add_f32_e32 v53, 1.0, v74
	v_rcp_f32_e32 v80, v53
	v_add_f32_e32 v53, 1.0, v75
	v_rcp_f32_e32 v81, v53
	v_pk_mul_f32 v[54:55], v[114:115], v[54:55]
	v_pk_fma_f32 v[108:109], v[182:183], v[104:105], v[162:163] op_sel:[1,0,0]
	v_pk_mul_f32 v[54:55], v[158:159], v[54:55]
	v_or_b32_e32 v53, 16, v52
	v_cvt_pk_bf16_f32 v74, v54, v55
	v_pk_mul_f32 v[54:55], v[112:113], v[80:81]
	v_pk_fma_f32 v[104:105], v[182:183], v[110:111], v[168:169] op_sel:[1,0,0]
	v_pk_mul_f32 v[54:55], v[156:157], v[54:55]
	v_pk_fma_f32 v[110:111], v[182:183], v[216:217], v[164:165] op_sel:[1,0,0]
	v_cvt_pk_bf16_f32 v75, v54, v55
	v_mad_i64_i32 v[54:55], s[10:11], v53, s66, v[6:7]
	v_mul_f32_e32 v53, 0xbfb8aa3b, v108
	v_lshl_add_u64 v[54:55], v[54:55], 0, v[8:9]
	v_exp_f32_e32 v53, v53
	v_mul_f32_e32 v80, 0xbfb8aa3b, v109
	v_exp_f32_e32 v80, v80
	global_store_dwordx4 v[54:55], v[72:75], off
	v_mul_f32_e32 v55, 0xbfb8aa3b, v110
	v_add_f32_e32 v53, 1.0, v53
	v_exp_f32_e32 v72, v55
	v_mul_f32_e32 v55, 0xbfb8aa3b, v111
	v_exp_f32_e32 v73, v55
	v_rcp_f32_e32 v54, v53
	v_add_f32_e32 v53, 1.0, v80
	v_rcp_f32_e32 v55, v53
	v_add_f32_e32 v53, 1.0, v72
	v_rcp_f32_e32 v74, v53
	v_add_f32_e32 v53, 1.0, v73
	v_rcp_f32_e32 v75, v53
	v_pk_mul_f32 v[54:55], v[108:109], v[54:55]
	v_mul_f32_e32 v53, 0xbfb8aa3b, v106
	v_pk_mul_f32 v[54:55], v[54:55], v[66:67]
	v_exp_f32_e32 v53, v53
	v_cvt_pk_bf16_f32 v72, v54, v55
	v_pk_mul_f32 v[54:55], v[110:111], v[74:75]
	v_pk_fma_f32 v[100:101], v[184:185], v[96:97], v[162:163] op_sel:[1,0,0]
	v_pk_mul_f32 v[54:55], v[54:55], v[64:65]
	v_mul_f32_e32 v64, 0xbfb8aa3b, v107
	v_exp_f32_e32 v64, v64
	v_cvt_pk_bf16_f32 v73, v54, v55
	v_add_f32_e32 v53, 1.0, v53
	v_mul_f32_e32 v55, 0xbfb8aa3b, v104
	v_rcp_f32_e32 v54, v53
	v_add_f32_e32 v53, 1.0, v64
	v_exp_f32_e32 v64, v55
	v_mul_f32_e32 v55, 0xbfb8aa3b, v105
	v_exp_f32_e32 v65, v55
	v_rcp_f32_e32 v55, v53
	v_add_f32_e32 v53, 1.0, v64
	v_rcp_f32_e32 v64, v53
	v_add_f32_e32 v53, 1.0, v65
	v_rcp_f32_e32 v65, v53
	v_pk_mul_f32 v[54:55], v[106:107], v[54:55]
	v_pk_fma_f32 v[96:97], v[184:185], v[102:103], v[168:169] op_sel:[1,0,0]
	v_pk_mul_f32 v[46:47], v[46:47], v[54:55]
	v_pk_fma_f32 v[102:103], v[184:185], v[218:219], v[164:165] op_sel:[1,0,0]
	v_cvt_pk_bf16_f32 v74, v46, v47
	v_pk_mul_f32 v[46:47], v[104:105], v[64:65]
	v_pk_fma_f32 v[98:99], v[184:185], v[190:191], v[166:167] op_sel:[1,0,0]
	v_pk_mul_f32 v[44:45], v[44:45], v[46:47]
	v_mul_f32_e32 v46, 0xbfb8aa3b, v100
	v_mul_f32_e32 v47, 0xbfb8aa3b, v101
	v_exp_f32_e32 v46, v46
	v_exp_f32_e32 v47, v47
	v_cvt_pk_bf16_f32 v75, v44, v45
	v_or_b32_e32 v44, 32, v52
	v_mad_i64_i32 v[44:45], s[10:11], v44, s66, v[6:7]
	v_lshl_add_u64 v[44:45], v[44:45], 0, v[8:9]
	global_store_dwordx4 v[44:45], v[72:75], off
	v_add_f32_e32 v44, 1.0, v46
	v_add_f32_e32 v45, 1.0, v47
; #define GASP __attribute__((address_space(1)))
; __device__ __forceinline__ float silu_f(float g) { return g * frcp(1.f + fexp2(-g * LOG2E)); }
;     __device__ __forceinline__ void operator()(Acc& acc, const Unit& u, int wr, int wc, int fr, int fq, LAS unsigned char* lds) const {
;     ...
;         for (int ai = 0; ai < 2; ++ai)
; #pragma unroll
;             for (int m = 0; m < 4; ++m) {
;                 const f32x4 g0 = acc[ai][0][m][0], g1 = acc[ai][0][m][1], u0 = acc[ai][1][m][0], u1 = acc[ai][1][m][1];
;                 u32x4 w;
;                 w.x = pk2(silu_f(g0[0]) * u0[0], silu_f(g0[1]) * u0[1]); w.y = pk2(silu_f(g0[2]) * u0[2], silu_f(g0[3]) * u0[3]);
;                 w.z = pk2(silu_f(g1[0]) * u1[0], silu_f(g1[1]) * u1[1]); w.w = pk2(silu_f(g1[2]) * u1[2], silu_f(g1[3]) * u1[3]);
;                 *(GASP u32x4*)(O + (size_t)(row0 + ai * HALF + m * 16) * FF + col0) = w;
	v_mul_f32_e32 v46, 0xbfb8aa3b, v102
	v_mul_f32_e32 v47, 0xbfb8aa3b, v103
	v_rcp_f32_e32 v44, v44
	v_exp_f32_e32 v46, v46
	v_exp_f32_e32 v47, v47
	v_rcp_f32_e32 v45, v45
	v_pk_fma_f32 v[92:93], v[186:187], v[88:89], v[162:163] op_sel:[1,0,0]
	v_add_f32_e32 v46, 1.0, v46
	v_add_f32_e32 v47, 1.0, v47
	v_pk_mul_f32 v[44:45], v[100:101], v[44:45]
	v_rcp_f32_e32 v46, v46
	v_rcp_f32_e32 v47, v47
	v_pk_mul_f32 v[44:45], v[44:45], v[58:59]
	v_pk_fma_f32 v[88:89], v[186:187], v[94:95], v[168:169] op_sel:[1,0,0]
	v_cvt_pk_bf16_f32 v44, v44, v45
	v_mul_f32_e32 v45, 0xbfb8aa3b, v98
	v_exp_f32_e32 v53, v45
	v_mul_f32_e32 v45, 0xbfb8aa3b, v99
	v_exp_f32_e32 v54, v45
	v_pk_mul_f32 v[46:47], v[102:103], v[46:47]
	v_pk_fma_f32 v[94:95], v[186:187], v[220:221], v[164:165] op_sel:[1,0,0]
	v_pk_mul_f32 v[46:47], v[46:47], v[56:57]
	v_pk_fma_f32 v[90:91], v[186:187], v[206:207], v[166:167] op_sel:[1,0,0]
	v_cvt_pk_bf16_f32 v45, v46, v47
	v_add_f32_e32 v46, 1.0, v53
	v_mul_f32_e32 v53, 0xbfb8aa3b, v96
	v_add_f32_e32 v47, 1.0, v54
	v_exp_f32_e32 v53, v53
	v_mul_f32_e32 v54, 0xbfb8aa3b, v97
	v_exp_f32_e32 v55, v54
	v_rcp_f32_e32 v46, v46
	v_rcp_f32_e32 v47, v47
	v_add_f32_e32 v53, 1.0, v53
	v_rcp_f32_e32 v54, v53
	v_add_f32_e32 v53, 1.0, v55
	v_rcp_f32_e32 v55, v53
	v_pk_mul_f32 v[46:47], v[98:99], v[46:47]
	v_pk_fma_f32 v[84:85], v[188:189], v[76:77], v[162:163] op_sel:[1,0,0]
	v_pk_mul_f32 v[38:39], v[38:39], v[46:47]
	v_pk_fma_f32 v[76:77], v[188:189], v[86:87], v[168:169] op_sel:[1,0,0]
	v_cvt_pk_bf16_f32 v46, v38, v39
	v_pk_mul_f32 v[38:39], v[96:97], v[54:55]
	v_pk_fma_f32 v[86:87], v[188:189], v[222:223], v[164:165] op_sel:[1,0,0]
	v_pk_mul_f32 v[36:37], v[36:37], v[38:39]
	v_mul_f32_e32 v38, 0xbfb8aa3b, v94
	v_cvt_pk_bf16_f32 v47, v36, v37
	v_or_b32_e32 v36, 48, v52
	v_mad_i64_i32 v[36:37], s[10:11], v36, s66, v[6:7]
	v_lshl_add_u64 v[36:37], v[36:37], 0, v[8:9]
	global_store_dwordx4 v[36:37], v[44:47], off
	v_mul_f32_e32 v36, 0xbfb8aa3b, v92
	v_mul_f32_e32 v37, 0xbfb8aa3b, v93
	v_exp_f32_e32 v36, v36
	v_exp_f32_e32 v37, v37
	v_mul_f32_e32 v39, 0xbfb8aa3b, v95
	v_exp_f32_e32 v38, v38
	v_exp_f32_e32 v39, v39
	v_add_f32_e32 v36, 1.0, v36
	v_add_f32_e32 v37, 1.0, v37
	v_rcp_f32_e32 v36, v36
	v_rcp_f32_e32 v37, v37
	v_add_f32_e32 v38, 1.0, v38
	v_add_f32_e32 v39, 1.0, v39
	v_rcp_f32_e32 v38, v38
	v_rcp_f32_e32 v39, v39
	v_pk_mul_f32 v[36:37], v[92:93], v[36:37]
	v_add_u32_e32 v44, 0x80, v52
	v_pk_mul_f32 v[34:35], v[34:35], v[36:37]
	v_pk_mul_f32 v[36:37], v[94:95], v[38:39]
	v_cvt_pk_bf16_f32 v34, v34, v35
	v_mul_f32_e32 v35, 0xbfb8aa3b, v90
	v_pk_mul_f32 v[32:33], v[32:33], v[36:37]
	v_exp_f32_e32 v36, v35
	v_mul_f32_e32 v35, 0xbfb8aa3b, v91
	v_exp_f32_e32 v37, v35
	v_cvt_pk_bf16_f32 v35, v32, v33
	v_add_f32_e32 v32, 1.0, v36
	v_mul_f32_e32 v36, 0xbfb8aa3b, v88
	v_add_f32_e32 v33, 1.0, v37
	v_exp_f32_e32 v36, v36
	v_mul_f32_e32 v37, 0xbfb8aa3b, v89
	v_exp_f32_e32 v37, v37
	v_rcp_f32_e32 v32, v32
	v_rcp_f32_e32 v33, v33
	v_add_f32_e32 v36, 1.0, v36
	v_rcp_f32_e32 v38, v36
	v_add_f32_e32 v36, 1.0, v37
	v_rcp_f32_e32 v39, v36
	v_pk_mul_f32 v[32:33], v[90:91], v[32:33]
	v_pk_fma_f32 v[78:79], v[188:189], v[210:211], v[166:167] op_sel:[1,0,0]
	v_pk_mul_f32 v[30:31], v[30:31], v[32:33]
	v_pk_fma_f32 v[68:69], v[194:195], v[68:69], v[162:163] op_sel:[1,0,0]
	v_cvt_pk_bf16_f32 v36, v30, v31
	v_pk_mul_f32 v[30:31], v[88:89], v[38:39]
	v_pk_fma_f32 v[70:71], v[194:195], v[70:71], v[164:165] op_sel:[1,0,0]
	v_pk_mul_f32 v[28:29], v[28:29], v[30:31]
	v_mul_f32_e32 v30, 0xbfb8aa3b, v84
	v_mul_f32_e32 v31, 0xbfb8aa3b, v85
	v_exp_f32_e32 v30, v30
	v_exp_f32_e32 v31, v31
	v_cvt_pk_bf16_f32 v37, v28, v29
	v_mad_i64_i32 v[28:29], s[10:11], v44, s66, v[6:7]
	v_lshl_add_u64 v[28:29], v[28:29], 0, v[8:9]
	global_store_dwordx4 v[28:29], v[34:37], off
	v_add_f32_e32 v28, 1.0, v30
	v_add_f32_e32 v29, 1.0, v31
	v_mul_f32_e32 v30, 0xbfb8aa3b, v86
	v_mul_f32_e32 v31, 0xbfb8aa3b, v87
	v_exp_f32_e32 v30, v30
	v_exp_f32_e32 v31, v31
	v_rcp_f32_e32 v28, v28
	v_rcp_f32_e32 v29, v29
	v_add_f32_e32 v30, 1.0, v30
	v_add_f32_e32 v31, 1.0, v31
	v_rcp_f32_e32 v30, v30
	v_rcp_f32_e32 v31, v31
	v_pk_mul_f32 v[28:29], v[84:85], v[28:29]
	v_pk_fma_f32 v[60:61], v[196:197], v[60:61], v[162:163] op_sel:[1,0,0]
	v_pk_mul_f32 v[26:27], v[26:27], v[28:29]
	v_pk_mul_f32 v[28:29], v[86:87], v[30:31]
; #define GASP __attribute__((address_space(1)))
; __device__ __forceinline__ float silu_f(float g) { return g * frcp(1.f + fexp2(-g * LOG2E)); }
; #define PG8_BAR __builtin_amdgcn_s_barrier()
; template <class Epi, class Sched, bool ALIGN_EPI = false, bool SP2 = false>
; __device__ __forceinline__ void gemm_phase(LAS unsigned char* lds, const Gemm g, const Sched& S, const Epi& E) {
;     ...
;         if (!has_next) break;
; #pragma unroll
;         for (int a = 0; a < 2; ++a)
; #pragma unroll
;             for (int b = 0; b < 2; ++b)
; #pragma unroll
;                 for (int m = 0; m < 4; ++m)
; #pragma unroll
;                     for (int n = 0; n < 2; ++n) acc[a][b][m][n] = (f32x4){0.f, 0.f, 0.f, 0.f};
;         cur = nxt; cA = nA; cB = nB; ++ui;
;         if constexpr (ALIGN_EPI) { if (wr == 1) PG8_BAR; }
;     __device__ __forceinline__ void operator()(Acc& acc, const Unit& u, int wr, int wc, int fr, int fq, LAS unsigned char* lds) const {
;     ...
;         for (int ai = 0; ai < 2; ++ai)
; #pragma unroll
;             for (int m = 0; m < 4; ++m) {
;                 const f32x4 g0 = acc[ai][0][m][0], g1 = acc[ai][0][m][1], u0 = acc[ai][1][m][0], u1 = acc[ai][1][m][1];
;                 u32x4 w;
;                 w.x = pk2(silu_f(g0[0]) * u0[0], silu_f(g0[1]) * u0[1]); w.y = pk2(silu_f(g0[2]) * u0[2], silu_f(g0[3]) * u0[3]);
;                 w.z = pk2(silu_f(g1[0]) * u1[0], silu_f(g1[1]) * u1[1]); w.w = pk2(silu_f(g1[2]) * u1[2], silu_f(g1[3]) * u1[3]);
;                 *(GASP u32x4*)(O + (size_t)(row0 + ai * HALF + m * 16) * FF + col0) = w;
	v_cvt_pk_bf16_f32 v26, v26, v27
	v_mul_f32_e32 v27, 0xbfb8aa3b, v78
	v_pk_mul_f32 v[24:25], v[24:25], v[28:29]
	v_exp_f32_e32 v28, v27
	v_mul_f32_e32 v27, 0xbfb8aa3b, v79
	v_exp_f32_e32 v29, v27
	v_cvt_pk_bf16_f32 v27, v24, v25
	v_add_f32_e32 v24, 1.0, v28
	v_mul_f32_e32 v28, 0xbfb8aa3b, v76
	v_add_f32_e32 v25, 1.0, v29
	v_exp_f32_e32 v28, v28
	v_mul_f32_e32 v29, 0xbfb8aa3b, v77
	v_exp_f32_e32 v29, v29
	v_rcp_f32_e32 v24, v24
	v_rcp_f32_e32 v25, v25
	v_add_f32_e32 v28, 1.0, v28
	v_rcp_f32_e32 v30, v28
	v_add_f32_e32 v28, 1.0, v29
	v_rcp_f32_e32 v31, v28
	v_pk_mul_f32 v[24:25], v[78:79], v[24:25]
	v_pk_fma_f32 v[62:63], v[196:197], v[62:63], v[164:165] op_sel:[1,0,0]
	v_pk_mul_f32 v[14:15], v[14:15], v[24:25]
	s_nop 0
	v_cvt_pk_bf16_f32 v28, v14, v15
	v_pk_mul_f32 v[14:15], v[76:77], v[30:31]
	s_nop 0
	v_pk_mul_f32 v[12:13], v[12:13], v[14:15]
	v_mul_f32_e32 v14, 0xbfb8aa3b, v68
	v_mul_f32_e32 v15, 0xbfb8aa3b, v69
	v_exp_f32_e32 v14, v14
	v_exp_f32_e32 v15, v15
	v_cvt_pk_bf16_f32 v29, v12, v13
	v_add_u32_e32 v12, 0x90, v52
	v_mad_i64_i32 v[12:13], s[10:11], v12, s66, v[6:7]
	v_lshl_add_u64 v[12:13], v[12:13], 0, v[8:9]
	global_store_dwordx4 v[12:13], v[26:29], off
	v_add_f32_e32 v12, 1.0, v14
	v_add_f32_e32 v13, 1.0, v15
	v_mul_f32_e32 v14, 0xbfb8aa3b, v70
	v_mul_f32_e32 v15, 0xbfb8aa3b, v71
	v_exp_f32_e32 v14, v14
	v_exp_f32_e32 v15, v15
	v_rcp_f32_e32 v12, v12
	v_rcp_f32_e32 v13, v13
	v_add_f32_e32 v14, 1.0, v14
	v_add_f32_e32 v15, 1.0, v15
	v_rcp_f32_e32 v14, v14
	v_rcp_f32_e32 v15, v15
	v_pk_mul_f32 v[12:13], v[68:69], v[12:13]
	v_pk_mul_f32 v[14:15], v[70:71], v[14:15]
	v_pk_mul_f32 v[12:13], v[22:23], v[12:13]
	v_pk_mul_f32 v[14:15], v[20:21], v[14:15]
	v_cvt_pk_bf16_f32 v12, v12, v13
	v_mul_f32_e32 v13, 0xbfb8aa3b, v50
	v_exp_f32_e32 v20, v13
	v_mul_f32_e32 v13, 0xbfb8aa3b, v51
	v_exp_f32_e32 v21, v13
	v_cvt_pk_bf16_f32 v13, v14, v15
	v_add_f32_e32 v14, 1.0, v20
	v_mul_f32_e32 v20, 0xbfb8aa3b, v48
	v_add_f32_e32 v15, 1.0, v21
	v_mul_f32_e32 v21, 0xbfb8aa3b, v49
	v_exp_f32_e32 v20, v20
	v_exp_f32_e32 v21, v21
	v_rcp_f32_e32 v14, v14
	v_rcp_f32_e32 v15, v15
	v_add_f32_e32 v20, 1.0, v20
	v_add_f32_e32 v21, 1.0, v21
	v_rcp_f32_e32 v20, v20
	v_rcp_f32_e32 v21, v21
	v_pk_mul_f32 v[14:15], v[50:51], v[14:15]
	s_nop 0
	v_pk_mul_f32 v[10:11], v[10:11], v[14:15]
	s_nop 0
	v_cvt_pk_bf16_f32 v14, v10, v11
	v_pk_mul_f32 v[10:11], v[48:49], v[20:21]
	s_nop 0
	v_pk_mul_f32 v[4:5], v[4:5], v[10:11]
	v_mul_f32_e32 v10, 0xbfb8aa3b, v60
	v_exp_f32_e32 v10, v10
	v_mul_f32_e32 v11, 0xbfb8aa3b, v61
	v_cvt_pk_bf16_f32 v15, v4, v5
	v_add_u32_e32 v4, 0xa0, v52
	v_exp_f32_e32 v11, v11
	v_mad_i64_i32 v[4:5], s[10:11], v4, s66, v[6:7]
	v_lshl_add_u64 v[4:5], v[4:5], 0, v[8:9]
	global_store_dwordx4 v[4:5], v[12:15], off
	v_add_f32_e32 v4, 1.0, v10
	v_mul_f32_e32 v10, 0xbfb8aa3b, v62
	v_add_f32_e32 v5, 1.0, v11
	v_exp_f32_e32 v10, v10
	v_mul_f32_e32 v11, 0xbfb8aa3b, v63
	v_exp_f32_e32 v11, v11
	v_rcp_f32_e32 v4, v4
	v_rcp_f32_e32 v5, v5
	v_add_f32_e32 v10, 1.0, v10
	v_rcp_f32_e32 v12, v10
	v_add_f32_e32 v10, 1.0, v11
	v_rcp_f32_e32 v13, v10
	v_pk_mul_f32 v[4:5], v[60:61], v[4:5]
	v_mul_f32_e32 v11, 0xbfb8aa3b, v42
	v_pk_mul_f32 v[4:5], v[18:19], v[4:5]
	s_nop 0
	v_cvt_pk_bf16_f32 v10, v4, v5
	v_pk_mul_f32 v[4:5], v[62:63], v[12:13]
	v_exp_f32_e32 v12, v11
	v_mul_f32_e32 v11, 0xbfb8aa3b, v43
	v_exp_f32_e32 v13, v11
	v_pk_mul_f32 v[4:5], v[16:17], v[4:5]
	s_nop 0
	v_cvt_pk_bf16_f32 v11, v4, v5
	v_add_f32_e32 v4, 1.0, v12
	v_mul_f32_e32 v12, 0xbfb8aa3b, v40
	v_add_f32_e32 v5, 1.0, v13
	v_exp_f32_e32 v12, v12
	v_mul_f32_e32 v13, 0xbfb8aa3b, v41
	v_exp_f32_e32 v13, v13
	v_rcp_f32_e32 v4, v4
	v_rcp_f32_e32 v5, v5
	v_add_f32_e32 v12, 1.0, v12
	v_rcp_f32_e32 v14, v12
	v_add_f32_e32 v12, 1.0, v13
	v_rcp_f32_e32 v15, v12
	v_pk_mul_f32 v[4:5], v[42:43], v[4:5]
	s_nop 0
	v_pk_mul_f32 v[2:3], v[2:3], v[4:5]
	s_nop 0
	v_cvt_pk_bf16_f32 v12, v2, v3
	v_pk_mul_f32 v[2:3], v[40:41], v[14:15]
	s_nop 0
	v_pk_mul_f32 v[0:1], v[0:1], v[2:3]
	s_nop 0
	v_cvt_pk_bf16_f32 v13, v0, v1
	v_add_u32_e32 v0, 0xb0, v52
	v_mad_i64_i32 v[0:1], s[10:11], v0, s66, v[6:7]
	v_lshl_add_u64 v[0:1], v[0:1], 0, v[8:9]
	global_store_dwordx4 v[0:1], v[10:13], off
	s_cbranch_vccnz .LBB0_1564
	s_andn2_b64 vcc, exec, s[12:13]
	s_cbranch_vccnz .LBB0_1563
	s_barrier
	s_branch .LBB0_1563
